# kind 0 f32 gate-column tile and kind 4 transposed v tiles also written as straight epilogue blocks
# speedup vs baseline: 1.0269x; 1.0147x over previous
; DI void st8bf(bf16_t* dst, f32x4 v0, f32x4 v1) { u32x4 w; w.x = pk2(v0[0], v0[1]); w.y = pk2(v0[2], v0[3]); w.z = pk2(v1[0], v1[1]); w.w = pk2(v1[2], v1[3]); *(u32x4*)dst = w; }
;     DI void st(int row, int col, f32x4 v0, f32x4 v1) const {
;     ...
;         case EK_NSAIN: {
;             if (col < 1024) { st8bf(d0 + (size_t)row * 1024 + col, v0 * 0.18033688011112042f, v1 * 0.18033688011112042f);   }
;             else if (col < 2560) {
;                 const int cc0 = col - 1024, ts = cc0 >> 8, cc = cc0 & 255, g = cc >> 6, dd = cc & 63, b = row >> 11, t = row & 2047;
;                 bf16_t* base = d1 + (size_t)ts * (16 * MiB);
;                 if (ts == 3 || ts == 5) { bf16_t* d = base + ((size_t)(b * 4 + g) * 64 + dd) * 2048 + t;
; #pragma unroll
;                     for (int e = 0; e < 4; ++e) { d[(size_t)e * 2048] = f2bf(v0[e]); d[(size_t)(e + 4) * 2048] = f2bf(v1[e]); } }
;                 else st8bf(base + ((size_t)(b * 4 + g) * 2048 + t) * 64 + dd, v0, v1);
.Lnsa_epi:
	s_cmp_lt_u32 s70, 4
	s_cbranch_scc1 .Lnsa_q
	s_cmp_eq_u32 s70, 7
	s_cbranch_scc1 .Lnsa_t
	s_cmp_eq_u32 s70, 9
	s_cbranch_scc1 .Lnsa_t
	s_cmp_gt_u32 s70, 8
	s_cbranch_scc1 .Lnsa_back
	s_sub_i32 s71, s70, 4
	s_lshl_b32 s71, s71, 25
	s_add_u32 s76, s14, s71
	s_addc_u32 s77, s15, 0
	s_lshr_b32 s71, s36, 3
	s_lshl_b32 s71, s71, 20
	s_and_b32 s80, s36, 7
	s_lshl_b32 s80, s80, 15
	s_add_u32 s71, s71, s80
	s_add_u32 s76, s76, s71
	s_addc_u32 s77, s77, 0
	v_lshrrev_b32_e32 v228, 6, v194
	v_lshlrev_b32_e32 v228, 18, v228
	v_lshl_add_u32 v228, v183, 7, v228
	v_and_b32_e32 v229, 63, v194
	v_lshl_add_u32 v228, v229, 1, v228
	v_add_u32_e32 v229, 0x80000, v228
	s_movk_i32 s81, 0x800
	s_movk_i32 s80, 0x2800
	v_cvt_pk_bf16_f32 v128, v124, v125
	v_cvt_pk_bf16_f32 v129, v126, v127
	v_cvt_pk_bf16_f32 v130, v120, v121
	v_cvt_pk_bf16_f32 v131, v122, v123
	global_store_dwordx4 v228, v[128:131], s[76:77]
	v_cvt_pk_bf16_f32 v132, v112, v113
	v_cvt_pk_bf16_f32 v133, v114, v115
	v_cvt_pk_bf16_f32 v134, v108, v109
	v_cvt_pk_bf16_f32 v135, v110, v111
	global_store_dwordx4 v229, v[132:135], s[76:77]
	s_add_u32 s76, s76, s81
	s_addc_u32 s77, s77, 0
	v_cvt_pk_bf16_f32 v136, v116, v117
	v_cvt_pk_bf16_f32 v137, v118, v119
	v_cvt_pk_bf16_f32 v138, v104, v105
	v_cvt_pk_bf16_f32 v139, v106, v107
	global_store_dwordx4 v228, v[136:139], s[76:77]
	v_cvt_pk_bf16_f32 v140, v96, v97
	v_cvt_pk_bf16_f32 v141, v98, v99
	v_cvt_pk_bf16_f32 v142, v92, v93
	v_cvt_pk_bf16_f32 v143, v94, v95
	global_store_dwordx4 v229, v[140:143], s[76:77]
	s_add_u32 s76, s76, s81
	s_addc_u32 s77, s77, 0
	v_cvt_pk_bf16_f32 v128, v100, v101
	v_cvt_pk_bf16_f32 v129, v102, v103
	v_cvt_pk_bf16_f32 v130, v88, v89
	v_cvt_pk_bf16_f32 v131, v90, v91
	global_store_dwordx4 v228, v[128:131], s[76:77]
	v_cvt_pk_bf16_f32 v132, v80, v81
	v_cvt_pk_bf16_f32 v133, v82, v83
	v_cvt_pk_bf16_f32 v134, v76, v77
	v_cvt_pk_bf16_f32 v135, v78, v79
	global_store_dwordx4 v229, v[132:135], s[76:77]
	s_add_u32 s76, s76, s81
	s_addc_u32 s77, s77, 0
	v_cvt_pk_bf16_f32 v136, v84, v85
	v_cvt_pk_bf16_f32 v137, v86, v87
	v_cvt_pk_bf16_f32 v138, v72, v73
	v_cvt_pk_bf16_f32 v139, v74, v75
	global_store_dwordx4 v228, v[136:139], s[76:77]
	v_cvt_pk_bf16_f32 v140, v68, v69
	v_cvt_pk_bf16_f32 v141, v70, v71
	v_cvt_pk_bf16_f32 v142, v64, v65
	v_cvt_pk_bf16_f32 v143, v66, v67
	global_store_dwordx4 v229, v[140:143], s[76:77]
	s_add_u32 s76, s76, s80
	s_addc_u32 s77, s77, 0
	v_cvt_pk_bf16_f32 v128, v60, v61
	v_cvt_pk_bf16_f32 v129, v62, v63
	v_cvt_pk_bf16_f32 v130, v56, v57
	v_cvt_pk_bf16_f32 v131, v58, v59
	global_store_dwordx4 v228, v[128:131], s[76:77]
	v_cvt_pk_bf16_f32 v132, v48, v49
	v_cvt_pk_bf16_f32 v133, v50, v51
	v_cvt_pk_bf16_f32 v134, v44, v45
	v_cvt_pk_bf16_f32 v135, v46, v47
	global_store_dwordx4 v229, v[132:135], s[76:77]
	s_add_u32 s76, s76, s81
	s_addc_u32 s77, s77, 0
	v_cvt_pk_bf16_f32 v136, v52, v53
	v_cvt_pk_bf16_f32 v137, v54, v55
	v_cvt_pk_bf16_f32 v138, v40, v41
	v_cvt_pk_bf16_f32 v139, v42, v43
	global_store_dwordx4 v228, v[136:139], s[76:77]
	v_cvt_pk_bf16_f32 v140, v24, v25
	v_cvt_pk_bf16_f32 v141, v26, v27
	v_cvt_pk_bf16_f32 v142, v20, v21
	v_cvt_pk_bf16_f32 v143, v22, v23
	global_store_dwordx4 v229, v[140:143], s[76:77]
	s_add_u32 s76, s76, s81
	s_addc_u32 s77, s77, 0
	v_cvt_pk_bf16_f32 v128, v36, v37
	v_cvt_pk_bf16_f32 v129, v38, v39
	v_cvt_pk_bf16_f32 v130, v16, v17
	v_cvt_pk_bf16_f32 v131, v18, v19
	global_store_dwordx4 v228, v[128:131], s[76:77]
	v_cvt_pk_bf16_f32 v132, v28, v29
	v_cvt_pk_bf16_f32 v133, v30, v31
	v_cvt_pk_bf16_f32 v134, v32, v33
	v_cvt_pk_bf16_f32 v135, v34, v35
	global_store_dwordx4 v229, v[132:135], s[76:77]
	s_add_u32 s76, s76, s81
	s_addc_u32 s77, s77, 0
	v_cvt_pk_bf16_f32 v136, v12, v13
	v_cvt_pk_bf16_f32 v137, v14, v15
	v_cvt_pk_bf16_f32 v138, v0, v1
	v_cvt_pk_bf16_f32 v139, v2, v3
	global_store_dwordx4 v228, v[136:139], s[76:77]
	v_cvt_pk_bf16_f32 v140, v8, v9
	v_cvt_pk_bf16_f32 v141, v10, v11
	v_cvt_pk_bf16_f32 v142, v4, v5
	v_cvt_pk_bf16_f32 v143, v6, v7
	global_store_dwordx4 v229, v[140:143], s[76:77]
	s_branch .Lnsa_done
.Lnsa_q:
	s_lshl_b32 s71, s36, 19
	s_lshl_b32 s80, s70, 9
	s_add_u32 s71, s71, s80
	s_add_u32 s76, s12, s71
	s_addc_u32 s77, s13, 0
	v_lshlrev_b32_e32 v229, 1, v194
	v_lshl_add_u32 v228, v183, 11, v229
	s_mov_b32 s98, 0x3e38aa3b
	s_mov_b32 s99, 0x3e38aa3b
	s_mov_b32 s81, 0x8000
	s_mov_b32 s80, 0x28000
	v_pk_mul_f32 v[124:125], v[124:125], s[98:99]
	v_pk_mul_f32 v[126:127], v[126:127], s[98:99]
	v_pk_mul_f32 v[120:121], v[120:121], s[98:99]
	v_pk_mul_f32 v[122:123], v[122:123], s[98:99]
	v_cvt_pk_bf16_f32 v128, v124, v125
	v_cvt_pk_bf16_f32 v129, v126, v127
	v_cvt_pk_bf16_f32 v130, v120, v121
	v_cvt_pk_bf16_f32 v131, v122, v123
	global_store_dwordx4 v228, v[128:131], s[76:77]
	v_pk_mul_f32 v[112:113], v[112:113], s[98:99]
	v_pk_mul_f32 v[114:115], v[114:115], s[98:99]
	v_pk_mul_f32 v[108:109], v[108:109], s[98:99]
	v_pk_mul_f32 v[110:111], v[110:111], s[98:99]
	v_cvt_pk_bf16_f32 v132, v112, v113
	v_cvt_pk_bf16_f32 v133, v114, v115
	v_cvt_pk_bf16_f32 v134, v108, v109
	v_cvt_pk_bf16_f32 v135, v110, v111
	global_store_dwordx4 v228, v[132:135], s[76:77] offset:256
	s_add_u32 s76, s76, s81
	s_addc_u32 s77, s77, 0
	v_pk_mul_f32 v[116:117], v[116:117], s[98:99]
	v_pk_mul_f32 v[118:119], v[118:119], s[98:99]
	v_pk_mul_f32 v[104:105], v[104:105], s[98:99]
	v_pk_mul_f32 v[106:107], v[106:107], s[98:99]
	v_cvt_pk_bf16_f32 v136, v116, v117
	v_cvt_pk_bf16_f32 v137, v118, v119
	v_cvt_pk_bf16_f32 v138, v104, v105
	v_cvt_pk_bf16_f32 v139, v106, v107
	global_store_dwordx4 v228, v[136:139], s[76:77]
	v_pk_mul_f32 v[96:97], v[96:97], s[98:99]
	v_pk_mul_f32 v[98:99], v[98:99], s[98:99]
; DI void st8bf(bf16_t* dst, f32x4 v0, f32x4 v1) { u32x4 w; w.x = pk2(v0[0], v0[1]); w.y = pk2(v0[2], v0[3]); w.z = pk2(v1[0], v1[1]); w.w = pk2(v1[2], v1[3]); *(u32x4*)dst = w; }
;     DI void st(int row, int col, f32x4 v0, f32x4 v1) const {
;     ...
;         case EK_NSAIN: {
;             if (col < 1024) { st8bf(d0 + (size_t)row * 1024 + col, v0 * 0.18033688011112042f, v1 * 0.18033688011112042f);   }
	v_pk_mul_f32 v[92:93], v[92:93], s[98:99]
	v_pk_mul_f32 v[94:95], v[94:95], s[98:99]
	v_cvt_pk_bf16_f32 v140, v96, v97
	v_cvt_pk_bf16_f32 v141, v98, v99
	v_cvt_pk_bf16_f32 v142, v92, v93
	v_cvt_pk_bf16_f32 v143, v94, v95
	global_store_dwordx4 v228, v[140:143], s[76:77] offset:256
	s_add_u32 s76, s76, s81
	s_addc_u32 s77, s77, 0
	v_pk_mul_f32 v[100:101], v[100:101], s[98:99]
	v_pk_mul_f32 v[102:103], v[102:103], s[98:99]
	v_pk_mul_f32 v[88:89], v[88:89], s[98:99]
	v_pk_mul_f32 v[90:91], v[90:91], s[98:99]
	v_cvt_pk_bf16_f32 v128, v100, v101
	v_cvt_pk_bf16_f32 v129, v102, v103
	v_cvt_pk_bf16_f32 v130, v88, v89
	v_cvt_pk_bf16_f32 v131, v90, v91
	global_store_dwordx4 v228, v[128:131], s[76:77]
	v_pk_mul_f32 v[80:81], v[80:81], s[98:99]
	v_pk_mul_f32 v[82:83], v[82:83], s[98:99]
	v_pk_mul_f32 v[76:77], v[76:77], s[98:99]
	v_pk_mul_f32 v[78:79], v[78:79], s[98:99]
	v_cvt_pk_bf16_f32 v132, v80, v81
	v_cvt_pk_bf16_f32 v133, v82, v83
	v_cvt_pk_bf16_f32 v134, v76, v77
	v_cvt_pk_bf16_f32 v135, v78, v79
	global_store_dwordx4 v228, v[132:135], s[76:77] offset:256
	s_add_u32 s76, s76, s81
	s_addc_u32 s77, s77, 0
	v_pk_mul_f32 v[84:85], v[84:85], s[98:99]
	v_pk_mul_f32 v[86:87], v[86:87], s[98:99]
	v_pk_mul_f32 v[72:73], v[72:73], s[98:99]
	v_pk_mul_f32 v[74:75], v[74:75], s[98:99]
	v_cvt_pk_bf16_f32 v136, v84, v85
	v_cvt_pk_bf16_f32 v137, v86, v87
	v_cvt_pk_bf16_f32 v138, v72, v73
	v_cvt_pk_bf16_f32 v139, v74, v75
	global_store_dwordx4 v228, v[136:139], s[76:77]
	v_pk_mul_f32 v[68:69], v[68:69], s[98:99]
	v_pk_mul_f32 v[70:71], v[70:71], s[98:99]
	v_pk_mul_f32 v[64:65], v[64:65], s[98:99]
	v_pk_mul_f32 v[66:67], v[66:67], s[98:99]
	v_cvt_pk_bf16_f32 v140, v68, v69
	v_cvt_pk_bf16_f32 v141, v70, v71
	v_cvt_pk_bf16_f32 v142, v64, v65
	v_cvt_pk_bf16_f32 v143, v66, v67
	global_store_dwordx4 v228, v[140:143], s[76:77] offset:256
	s_add_u32 s76, s76, s80
	s_addc_u32 s77, s77, 0
	v_pk_mul_f32 v[60:61], v[60:61], s[98:99]
	v_pk_mul_f32 v[62:63], v[62:63], s[98:99]
	v_pk_mul_f32 v[56:57], v[56:57], s[98:99]
	v_pk_mul_f32 v[58:59], v[58:59], s[98:99]
	v_cvt_pk_bf16_f32 v128, v60, v61
	v_cvt_pk_bf16_f32 v129, v62, v63
	v_cvt_pk_bf16_f32 v130, v56, v57
	v_cvt_pk_bf16_f32 v131, v58, v59
	global_store_dwordx4 v228, v[128:131], s[76:77]
	v_pk_mul_f32 v[48:49], v[48:49], s[98:99]
	v_pk_mul_f32 v[50:51], v[50:51], s[98:99]
	v_pk_mul_f32 v[44:45], v[44:45], s[98:99]
	v_pk_mul_f32 v[46:47], v[46:47], s[98:99]
	v_cvt_pk_bf16_f32 v132, v48, v49
	v_cvt_pk_bf16_f32 v133, v50, v51
	v_cvt_pk_bf16_f32 v134, v44, v45
	v_cvt_pk_bf16_f32 v135, v46, v47
	global_store_dwordx4 v228, v[132:135], s[76:77] offset:256
	s_add_u32 s76, s76, s81
	s_addc_u32 s77, s77, 0
	v_pk_mul_f32 v[52:53], v[52:53], s[98:99]
	v_pk_mul_f32 v[54:55], v[54:55], s[98:99]
	v_pk_mul_f32 v[40:41], v[40:41], s[98:99]
	v_pk_mul_f32 v[42:43], v[42:43], s[98:99]
	v_cvt_pk_bf16_f32 v136, v52, v53
	v_cvt_pk_bf16_f32 v137, v54, v55
	v_cvt_pk_bf16_f32 v138, v40, v41
	v_cvt_pk_bf16_f32 v139, v42, v43
	global_store_dwordx4 v228, v[136:139], s[76:77]
	v_pk_mul_f32 v[24:25], v[24:25], s[98:99]
	v_pk_mul_f32 v[26:27], v[26:27], s[98:99]
	v_pk_mul_f32 v[20:21], v[20:21], s[98:99]
	v_pk_mul_f32 v[22:23], v[22:23], s[98:99]
	v_cvt_pk_bf16_f32 v140, v24, v25
	v_cvt_pk_bf16_f32 v141, v26, v27
	v_cvt_pk_bf16_f32 v142, v20, v21
	v_cvt_pk_bf16_f32 v143, v22, v23
	global_store_dwordx4 v228, v[140:143], s[76:77] offset:256
	s_add_u32 s76, s76, s81
	s_addc_u32 s77, s77, 0
	v_pk_mul_f32 v[36:37], v[36:37], s[98:99]
	v_pk_mul_f32 v[38:39], v[38:39], s[98:99]
	v_pk_mul_f32 v[16:17], v[16:17], s[98:99]
	v_pk_mul_f32 v[18:19], v[18:19], s[98:99]
	v_cvt_pk_bf16_f32 v128, v36, v37
	v_cvt_pk_bf16_f32 v129, v38, v39
	v_cvt_pk_bf16_f32 v130, v16, v17
	v_cvt_pk_bf16_f32 v131, v18, v19
	global_store_dwordx4 v228, v[128:131], s[76:77]
	v_pk_mul_f32 v[28:29], v[28:29], s[98:99]
	v_pk_mul_f32 v[30:31], v[30:31], s[98:99]
	v_pk_mul_f32 v[32:33], v[32:33], s[98:99]
	v_pk_mul_f32 v[34:35], v[34:35], s[98:99]
	v_cvt_pk_bf16_f32 v132, v28, v29
	v_cvt_pk_bf16_f32 v133, v30, v31
	v_cvt_pk_bf16_f32 v134, v32, v33
	v_cvt_pk_bf16_f32 v135, v34, v35
	global_store_dwordx4 v228, v[132:135], s[76:77] offset:256
	s_add_u32 s76, s76, s81
	s_addc_u32 s77, s77, 0
	v_pk_mul_f32 v[12:13], v[12:13], s[98:99]
	v_pk_mul_f32 v[14:15], v[14:15], s[98:99]
	v_pk_mul_f32 v[0:1], v[0:1], s[98:99]
	v_pk_mul_f32 v[2:3], v[2:3], s[98:99]
	v_cvt_pk_bf16_f32 v136, v12, v13
	v_cvt_pk_bf16_f32 v137, v14, v15
	v_cvt_pk_bf16_f32 v138, v0, v1
	v_cvt_pk_bf16_f32 v139, v2, v3
	global_store_dwordx4 v228, v[136:139], s[76:77]
	v_pk_mul_f32 v[8:9], v[8:9], s[98:99]
	v_pk_mul_f32 v[10:11], v[10:11], s[98:99]
	v_pk_mul_f32 v[4:5], v[4:5], s[98:99]
	v_pk_mul_f32 v[6:7], v[6:7], s[98:99]
	v_cvt_pk_bf16_f32 v140, v8, v9
	v_cvt_pk_bf16_f32 v141, v10, v11
	v_cvt_pk_bf16_f32 v142, v4, v5
	v_cvt_pk_bf16_f32 v143, v6, v7
	global_store_dwordx4 v228, v[140:143], s[76:77] offset:256
	s_branch .Lnsa_done
;     DI void st(int row, int col, f32x4 v0, f32x4 v1) const {
;     ...
;                 if (ts == 3 || ts == 5) { bf16_t* d = base + ((size_t)(b * 4 + g) * 64 + dd) * 2048 + t;
; #pragma unroll
;                     for (int e = 0; e < 4; ++e) { d[(size_t)e * 2048] = f2bf(v0[e]); d[(size_t)(e + 4) * 2048] = f2bf(v1[e]); } }
.Lnsa_t:
	s_sub_i32 s71, s70, 4
	s_lshl_b32 s71, s71, 25
	s_add_u32 s76, s14, s71
	s_addc_u32 s77, s15, 0
	s_lshr_b32 s71, s36, 3
	s_lshl_b32 s71, s71, 20
	s_and_b32 s80, s36, 7
	s_lshl_b32 s80, s80, 9
	s_add_u32 s71, s71, s80
	s_add_u32 s76, s76, s71
	s_addc_u32 s77, s77, 0
	s_add_u32 s80, s76, 0x1000
	s_addc_u32 s81, s77, 0
	s_add_u32 s98, s76, 0x2000
	s_addc_u32 s99, s77, 0
	s_add_u32 s100, s76, 0x3000
	s_addc_u32 s101, s77, 0
	v_lshrrev_b32_e32 v224, 6, v194
	v_lshlrev_b32_e32 v224, 18, v224
	v_and_b32_e32 v225, 63, v194
	v_lshl_add_u32 v224, v225, 12, v224
	v_lshl_add_u32 v224, v183, 1, v224
	v_add_u32_e32 v225, 0x80000, v224
	v_add_u32_e32 v226, 0x4000, v224
	v_add_u32_e32 v227, 0x4000, v225
	v_cvt_pk_bf16_f32 v128, v124, v120
	global_store_short v224, v128, s[76:77]
	global_store_short_d16_hi v226, v128, s[76:77]
	v_cvt_pk_bf16_f32 v129, v125, v121
	global_store_short v224, v129, s[80:81]
	global_store_short_d16_hi v226, v129, s[80:81]
	v_cvt_pk_bf16_f32 v130, v126, v122
	global_store_short v224, v130, s[98:99]
	global_store_short_d16_hi v226, v130, s[98:99]
	v_cvt_pk_bf16_f32 v131, v127, v123
	global_store_short v224, v131, s[100:101]
	global_store_short_d16_hi v226, v131, s[100:101]
	v_cvt_pk_bf16_f32 v132, v112, v108
	global_store_short v225, v132, s[76:77]
	global_store_short_d16_hi v227, v132, s[76:77]
	v_cvt_pk_bf16_f32 v133, v113, v109
	global_store_short v225, v133, s[80:81]
	global_store_short_d16_hi v227, v133, s[80:81]
	v_cvt_pk_bf16_f32 v134, v114, v110
	global_store_short v225, v134, s[98:99]
	global_store_short_d16_hi v227, v134, s[98:99]
	v_cvt_pk_bf16_f32 v135, v115, v111
	global_store_short v225, v135, s[100:101]
	global_store_short_d16_hi v227, v135, s[100:101]
	v_cvt_pk_bf16_f32 v128, v116, v104
	global_store_short v224, v128, s[76:77] offset:32
	global_store_short_d16_hi v226, v128, s[76:77] offset:32
	v_cvt_pk_bf16_f32 v129, v117, v105
	global_store_short v224, v129, s[80:81] offset:32
	global_store_short_d16_hi v226, v129, s[80:81] offset:32
	v_cvt_pk_bf16_f32 v130, v118, v106
	global_store_short v224, v130, s[98:99] offset:32
	global_store_short_d16_hi v226, v130, s[98:99] offset:32
	v_cvt_pk_bf16_f32 v131, v119, v107
	global_store_short v224, v131, s[100:101] offset:32
	global_store_short_d16_hi v226, v131, s[100:101] offset:32
	v_cvt_pk_bf16_f32 v132, v96, v92
	global_store_short v225, v132, s[76:77] offset:32
	global_store_short_d16_hi v227, v132, s[76:77] offset:32
	v_cvt_pk_bf16_f32 v133, v97, v93
	global_store_short v225, v133, s[80:81] offset:32
	global_store_short_d16_hi v227, v133, s[80:81] offset:32
	v_cvt_pk_bf16_f32 v134, v98, v94
	global_store_short v225, v134, s[98:99] offset:32
	global_store_short_d16_hi v227, v134, s[98:99] offset:32
	v_cvt_pk_bf16_f32 v135, v99, v95
	global_store_short v225, v135, s[100:101] offset:32
	global_store_short_d16_hi v227, v135, s[100:101] offset:32
	v_cvt_pk_bf16_f32 v128, v100, v88
	global_store_short v224, v128, s[76:77] offset:64
	global_store_short_d16_hi v226, v128, s[76:77] offset:64
	v_cvt_pk_bf16_f32 v129, v101, v89
	global_store_short v224, v129, s[80:81] offset:64
	global_store_short_d16_hi v226, v129, s[80:81] offset:64
	v_cvt_pk_bf16_f32 v130, v102, v90
	global_store_short v224, v130, s[98:99] offset:64
	global_store_short_d16_hi v226, v130, s[98:99] offset:64
	v_cvt_pk_bf16_f32 v131, v103, v91
	global_store_short v224, v131, s[100:101] offset:64
	global_store_short_d16_hi v226, v131, s[100:101] offset:64
	v_cvt_pk_bf16_f32 v132, v80, v76
	global_store_short v225, v132, s[76:77] offset:64
	global_store_short_d16_hi v227, v132, s[76:77] offset:64
	v_cvt_pk_bf16_f32 v133, v81, v77
	global_store_short v225, v133, s[80:81] offset:64
	global_store_short_d16_hi v227, v133, s[80:81] offset:64
	v_cvt_pk_bf16_f32 v134, v82, v78
	global_store_short v225, v134, s[98:99] offset:64
	global_store_short_d16_hi v227, v134, s[98:99] offset:64
	v_cvt_pk_bf16_f32 v135, v83, v79
	global_store_short v225, v135, s[100:101] offset:64
	global_store_short_d16_hi v227, v135, s[100:101] offset:64
	v_cvt_pk_bf16_f32 v128, v84, v72
	global_store_short v224, v128, s[76:77] offset:96
	global_store_short_d16_hi v226, v128, s[76:77] offset:96
	v_cvt_pk_bf16_f32 v129, v85, v73
	global_store_short v224, v129, s[80:81] offset:96
	global_store_short_d16_hi v226, v129, s[80:81] offset:96
	v_cvt_pk_bf16_f32 v130, v86, v74
	global_store_short v224, v130, s[98:99] offset:96
	global_store_short_d16_hi v226, v130, s[98:99] offset:96
	v_cvt_pk_bf16_f32 v131, v87, v75
	global_store_short v224, v131, s[100:101] offset:96
	global_store_short_d16_hi v226, v131, s[100:101] offset:96
	v_cvt_pk_bf16_f32 v132, v68, v64
	global_store_short v225, v132, s[76:77] offset:96
	global_store_short_d16_hi v227, v132, s[76:77] offset:96
	v_cvt_pk_bf16_f32 v133, v69, v65
	global_store_short v225, v133, s[80:81] offset:96
	global_store_short_d16_hi v227, v133, s[80:81] offset:96
	v_cvt_pk_bf16_f32 v134, v70, v66
;     DI void st(int row, int col, f32x4 v0, f32x4 v1) const {
;     ...
;                 if (ts == 3 || ts == 5) { bf16_t* d = base + ((size_t)(b * 4 + g) * 64 + dd) * 2048 + t;
; #pragma unroll
;                     for (int e = 0; e < 4; ++e) { d[(size_t)e * 2048] = f2bf(v0[e]); d[(size_t)(e + 4) * 2048] = f2bf(v1[e]); } }
	global_store_short v225, v134, s[98:99] offset:96
	global_store_short_d16_hi v227, v134, s[98:99] offset:96
	v_cvt_pk_bf16_f32 v135, v71, v67
	global_store_short v225, v135, s[100:101] offset:96
	global_store_short_d16_hi v227, v135, s[100:101] offset:96
	v_cvt_pk_bf16_f32 v128, v60, v56
	global_store_short v224, v128, s[76:77] offset:256
	global_store_short_d16_hi v226, v128, s[76:77] offset:256
	v_cvt_pk_bf16_f32 v129, v61, v57
	global_store_short v224, v129, s[80:81] offset:256
	global_store_short_d16_hi v226, v129, s[80:81] offset:256
	v_cvt_pk_bf16_f32 v130, v62, v58
	global_store_short v224, v130, s[98:99] offset:256
	global_store_short_d16_hi v226, v130, s[98:99] offset:256
	v_cvt_pk_bf16_f32 v131, v63, v59
	global_store_short v224, v131, s[100:101] offset:256
	global_store_short_d16_hi v226, v131, s[100:101] offset:256
	v_cvt_pk_bf16_f32 v132, v48, v44
	global_store_short v225, v132, s[76:77] offset:256
	global_store_short_d16_hi v227, v132, s[76:77] offset:256
	v_cvt_pk_bf16_f32 v133, v49, v45
	global_store_short v225, v133, s[80:81] offset:256
	global_store_short_d16_hi v227, v133, s[80:81] offset:256
	v_cvt_pk_bf16_f32 v134, v50, v46
	global_store_short v225, v134, s[98:99] offset:256
	global_store_short_d16_hi v227, v134, s[98:99] offset:256
	v_cvt_pk_bf16_f32 v135, v51, v47
	global_store_short v225, v135, s[100:101] offset:256
	global_store_short_d16_hi v227, v135, s[100:101] offset:256
	v_cvt_pk_bf16_f32 v128, v52, v40
	global_store_short v224, v128, s[76:77] offset:288
	global_store_short_d16_hi v226, v128, s[76:77] offset:288
	v_cvt_pk_bf16_f32 v129, v53, v41
	global_store_short v224, v129, s[80:81] offset:288
	global_store_short_d16_hi v226, v129, s[80:81] offset:288
	v_cvt_pk_bf16_f32 v130, v54, v42
	global_store_short v224, v130, s[98:99] offset:288
	global_store_short_d16_hi v226, v130, s[98:99] offset:288
	v_cvt_pk_bf16_f32 v131, v55, v43
	global_store_short v224, v131, s[100:101] offset:288
	global_store_short_d16_hi v226, v131, s[100:101] offset:288
	v_cvt_pk_bf16_f32 v132, v24, v20
	global_store_short v225, v132, s[76:77] offset:288
	global_store_short_d16_hi v227, v132, s[76:77] offset:288
	v_cvt_pk_bf16_f32 v133, v25, v21
	global_store_short v225, v133, s[80:81] offset:288
	global_store_short_d16_hi v227, v133, s[80:81] offset:288
	v_cvt_pk_bf16_f32 v134, v26, v22
	global_store_short v225, v134, s[98:99] offset:288
	global_store_short_d16_hi v227, v134, s[98:99] offset:288
	v_cvt_pk_bf16_f32 v135, v27, v23
	global_store_short v225, v135, s[100:101] offset:288
	global_store_short_d16_hi v227, v135, s[100:101] offset:288
	v_cvt_pk_bf16_f32 v128, v36, v16
	global_store_short v224, v128, s[76:77] offset:320
	global_store_short_d16_hi v226, v128, s[76:77] offset:320
	v_cvt_pk_bf16_f32 v129, v37, v17
	global_store_short v224, v129, s[80:81] offset:320
	global_store_short_d16_hi v226, v129, s[80:81] offset:320
	v_cvt_pk_bf16_f32 v130, v38, v18
	global_store_short v224, v130, s[98:99] offset:320
	global_store_short_d16_hi v226, v130, s[98:99] offset:320
	v_cvt_pk_bf16_f32 v131, v39, v19
	global_store_short v224, v131, s[100:101] offset:320
	global_store_short_d16_hi v226, v131, s[100:101] offset:320
	v_cvt_pk_bf16_f32 v132, v28, v32
	global_store_short v225, v132, s[76:77] offset:320
	global_store_short_d16_hi v227, v132, s[76:77] offset:320
	v_cvt_pk_bf16_f32 v133, v29, v33
	global_store_short v225, v133, s[80:81] offset:320
	global_store_short_d16_hi v227, v133, s[80:81] offset:320
	v_cvt_pk_bf16_f32 v134, v30, v34
	global_store_short v225, v134, s[98:99] offset:320
	global_store_short_d16_hi v227, v134, s[98:99] offset:320
	v_cvt_pk_bf16_f32 v135, v31, v35
	global_store_short v225, v135, s[100:101] offset:320
	global_store_short_d16_hi v227, v135, s[100:101] offset:320
	v_cvt_pk_bf16_f32 v128, v12, v0
	global_store_short v224, v128, s[76:77] offset:352
	global_store_short_d16_hi v226, v128, s[76:77] offset:352
	v_cvt_pk_bf16_f32 v129, v13, v1
	global_store_short v224, v129, s[80:81] offset:352
	global_store_short_d16_hi v226, v129, s[80:81] offset:352
	v_cvt_pk_bf16_f32 v130, v14, v2
	global_store_short v224, v130, s[98:99] offset:352
	global_store_short_d16_hi v226, v130, s[98:99] offset:352
	v_cvt_pk_bf16_f32 v131, v15, v3
	global_store_short v224, v131, s[100:101] offset:352
	global_store_short_d16_hi v226, v131, s[100:101] offset:352
	v_cvt_pk_bf16_f32 v132, v8, v4
	global_store_short v225, v132, s[76:77] offset:352
	global_store_short_d16_hi v227, v132, s[76:77] offset:352
	v_cvt_pk_bf16_f32 v133, v9, v5
	global_store_short v225, v133, s[80:81] offset:352
	global_store_short_d16_hi v227, v133, s[80:81] offset:352
	v_cvt_pk_bf16_f32 v134, v10, v6
	global_store_short v225, v134, s[98:99] offset:352
	global_store_short_d16_hi v227, v134, s[98:99] offset:352
	v_cvt_pk_bf16_f32 v135, v11, v7
	global_store_short v225, v135, s[100:101] offset:352
	global_store_short_d16_hi v227, v135, s[100:101] offset:352

; DI void st8bf(bf16_t* dst, f32x4 v0, f32x4 v1) { u32x4 w; w.x = pk2(v0[0], v0[1]); w.y = pk2(v0[2], v0[3]); w.z = pk2(v1[0], v1[1]); w.w = pk2(v1[2], v1[3]); *(u32x4*)dst = w; }
;     DI void st(int row, int col, f32x4 v0, f32x4 v1) const {
;     ...
;         case EK_ABIN: {
;             if (col < 256) st8bf(d0 + (size_t)row * 256 + col, v0, v1);
;             else if (col < 2560) st8bf(d1 + (size_t)row * 2304 + (col - 256), v0, v1);
;             else if (col < 3328) st8bf(d2 + (size_t)row * 768 + (col - 2560), v0, v1);
;             else { const int cc = col - 3328; if (cc < 16) { float* d = f0 + (size_t)row * 16 + cc; *(f32x4*)d = v0; *(f32x4*)(d + 4) = v1; } } } break;
.Labin_go:
	s_lshl_b32 s71, s71, 8
	v_lshl_add_u32 v228, s36, 8, v183
	v_or_b32_e32 v229, s71, v194
	v_lshlrev_b32_e32 v229, 1, v229
	v_mad_u32_u24 v228, v228, s80, v229
	s_lshl_b32 s81, s80, 4
	s_mul_i32 s80, s81, 5
	v_cvt_pk_bf16_f32 v128, v124, v125
	v_cvt_pk_bf16_f32 v129, v126, v127
	v_cvt_pk_bf16_f32 v130, v120, v121
	v_cvt_pk_bf16_f32 v131, v122, v123
	global_store_dwordx4 v228, v[128:131], s[76:77]
	v_cvt_pk_bf16_f32 v132, v112, v113
	v_cvt_pk_bf16_f32 v133, v114, v115
	v_cvt_pk_bf16_f32 v134, v108, v109
	v_cvt_pk_bf16_f32 v135, v110, v111
	global_store_dwordx4 v228, v[132:135], s[76:77] offset:256
	s_add_u32 s76, s76, s81
	s_addc_u32 s77, s77, 0
	v_cvt_pk_bf16_f32 v136, v116, v117
	v_cvt_pk_bf16_f32 v137, v118, v119
	v_cvt_pk_bf16_f32 v138, v104, v105
	v_cvt_pk_bf16_f32 v139, v106, v107
	global_store_dwordx4 v228, v[136:139], s[76:77]
	v_cvt_pk_bf16_f32 v140, v96, v97
	v_cvt_pk_bf16_f32 v141, v98, v99
	v_cvt_pk_bf16_f32 v142, v92, v93
	v_cvt_pk_bf16_f32 v143, v94, v95
	global_store_dwordx4 v228, v[140:143], s[76:77] offset:256
	s_add_u32 s76, s76, s81
	s_addc_u32 s77, s77, 0
	v_cvt_pk_bf16_f32 v128, v100, v101
	v_cvt_pk_bf16_f32 v129, v102, v103
	v_cvt_pk_bf16_f32 v130, v88, v89
	v_cvt_pk_bf16_f32 v131, v90, v91
	global_store_dwordx4 v228, v[128:131], s[76:77]
	v_cvt_pk_bf16_f32 v132, v80, v81
	v_cvt_pk_bf16_f32 v133, v82, v83
	v_cvt_pk_bf16_f32 v134, v76, v77
	v_cvt_pk_bf16_f32 v135, v78, v79
	global_store_dwordx4 v228, v[132:135], s[76:77] offset:256
	s_add_u32 s76, s76, s81
	s_addc_u32 s77, s77, 0
	v_cvt_pk_bf16_f32 v136, v84, v85
	v_cvt_pk_bf16_f32 v137, v86, v87
	v_cvt_pk_bf16_f32 v138, v72, v73
	v_cvt_pk_bf16_f32 v139, v74, v75
	global_store_dwordx4 v228, v[136:139], s[76:77]
	v_cvt_pk_bf16_f32 v140, v68, v69
	v_cvt_pk_bf16_f32 v141, v70, v71
	v_cvt_pk_bf16_f32 v142, v64, v65
	v_cvt_pk_bf16_f32 v143, v66, v67
	global_store_dwordx4 v228, v[140:143], s[76:77] offset:256
	s_add_u32 s76, s76, s80
	s_addc_u32 s77, s77, 0
	v_cvt_pk_bf16_f32 v128, v60, v61
	v_cvt_pk_bf16_f32 v129, v62, v63
	v_cvt_pk_bf16_f32 v130, v56, v57
	v_cvt_pk_bf16_f32 v131, v58, v59
	global_store_dwordx4 v228, v[128:131], s[76:77]
	v_cvt_pk_bf16_f32 v132, v48, v49
	v_cvt_pk_bf16_f32 v133, v50, v51
	v_cvt_pk_bf16_f32 v134, v44, v45
	v_cvt_pk_bf16_f32 v135, v46, v47
	global_store_dwordx4 v228, v[132:135], s[76:77] offset:256
	s_add_u32 s76, s76, s81
	s_addc_u32 s77, s77, 0
	v_cvt_pk_bf16_f32 v136, v52, v53
	v_cvt_pk_bf16_f32 v137, v54, v55
	v_cvt_pk_bf16_f32 v138, v40, v41
	v_cvt_pk_bf16_f32 v139, v42, v43
	global_store_dwordx4 v228, v[136:139], s[76:77]
	v_cvt_pk_bf16_f32 v140, v24, v25
	v_cvt_pk_bf16_f32 v141, v26, v27
	v_cvt_pk_bf16_f32 v142, v20, v21
	v_cvt_pk_bf16_f32 v143, v22, v23
	global_store_dwordx4 v228, v[140:143], s[76:77] offset:256
	s_add_u32 s76, s76, s81
	s_addc_u32 s77, s77, 0
	v_cvt_pk_bf16_f32 v128, v36, v37
	v_cvt_pk_bf16_f32 v129, v38, v39
	v_cvt_pk_bf16_f32 v130, v16, v17
	v_cvt_pk_bf16_f32 v131, v18, v19
	global_store_dwordx4 v228, v[128:131], s[76:77]
	v_cvt_pk_bf16_f32 v132, v28, v29
	v_cvt_pk_bf16_f32 v133, v30, v31
	v_cvt_pk_bf16_f32 v134, v32, v33
	v_cvt_pk_bf16_f32 v135, v34, v35
	global_store_dwordx4 v228, v[132:135], s[76:77] offset:256
	s_add_u32 s76, s76, s81
	s_addc_u32 s77, s77, 0
	v_cvt_pk_bf16_f32 v136, v12, v13
	v_cvt_pk_bf16_f32 v137, v14, v15
	v_cvt_pk_bf16_f32 v138, v0, v1
	v_cvt_pk_bf16_f32 v139, v2, v3
	global_store_dwordx4 v228, v[136:139], s[76:77]
	v_cvt_pk_bf16_f32 v140, v8, v9
	v_cvt_pk_bf16_f32 v141, v10, v11
	v_cvt_pk_bf16_f32 v142, v4, v5
	v_cvt_pk_bf16_f32 v143, v6, v7
	global_store_dwordx4 v228, v[140:143], s[76:77] offset:256
	s_branch .Labin_done
.Labin_f32:
	v_cmp_gt_u32_e32 vcc, 16, v194
	s_and_saveexec_b64 s[80:81], vcc
	v_lshl_add_u32 v228, s36, 8, v183
	v_lshlrev_b32_e32 v228, 6, v228
	v_lshl_add_u32 v228, v194, 2, v228
	global_store_dwordx4 v228, v[124:127], s[8:9]
	global_store_dwordx4 v228, v[120:123], s[8:9] offset:16
	global_store_dwordx4 v228, v[116:119], s[8:9] offset:1024
	global_store_dwordx4 v228, v[104:107], s[8:9] offset:1040
	global_store_dwordx4 v228, v[100:103], s[8:9] offset:2048
	global_store_dwordx4 v228, v[88:91], s[8:9] offset:2064
	global_store_dwordx4 v228, v[84:87], s[8:9] offset:3072
	global_store_dwordx4 v228, v[72:75], s[8:9] offset:3088
	s_add_u32 s76, s8, 0x2000
	s_addc_u32 s77, s9, 0
	global_store_dwordx4 v228, v[60:63], s[76:77]
	global_store_dwordx4 v228, v[56:59], s[76:77] offset:16
	global_store_dwordx4 v228, v[52:55], s[76:77] offset:1024
	global_store_dwordx4 v228, v[40:43], s[76:77] offset:1040
	global_store_dwordx4 v228, v[36:39], s[76:77] offset:2048
	global_store_dwordx4 v228, v[16:19], s[76:77] offset:2064
	global_store_dwordx4 v228, v[12:15], s[76:77] offset:3072
	global_store_dwordx4 v228, v[0:3], s[76:77] offset:3088
	s_or_b64 exec, exec, s[80:81]
.Labin_done:
.LBB0_649:
	s_andn2_b64 vcc, exec, s[44:45]
	s_mov_b32 s70, s25
	s_mov_b32 s36, s69
	s_mov_b64 s[76:77], s[4:5]
	s_mov_b64 s[74:75], s[0:1]
	s_cbranch_vccz .LBB0_1601
